# attention rowmax max3 tree, negm copies removed; mla_prep gain vectors preloaded once per iteration, counted waits
# speedup vs baseline: 1.0365x; 1.0083x over previous
; __device__ __forceinline__ float bflo(unsigned w) { return __uint_as_float(w << 16); }
; __device__ __forceinline__ float bfhi(unsigned w) { return __uint_as_float(w & 0xffff0000u); }
; __device__ __forceinline__ float bf2f(bf16 v) { return __uint_as_float((unsigned)v << 16); }
; __device__ __forceinline__ unsigned pk2(float lo, float hi) { f32x2 v = {lo, hi}; bf16x2_t b = __builtin_convertvector(v, bf16x2_t); return __builtin_bit_cast(unsigned, b); }
; __device__ __forceinline__ void mla_prep(const Args& a, int vcu, int G, int lane, int wave) {
;     ...
;     for (int m0 = gw; m0 < MT; m0 += 4 * NGW) {
;         unsigned qw[4][3]; u32x2 kw4[4]; float x1[4], x2[4], cs[4], sn4[4];
; #pragma unroll
;         for (int qq = 0; qq < 4; ++qq) { const int m = m0 + qq * NGW, mm = m < MT ? m : m0; const bf16* zr = Z + (size_t)mm * ZW;
; #pragma unroll
;             for (int j = 0; j < 3; ++j) qw[qq][j] = ((const unsigned*)(zr + Z_CQ))[lane + 64 * j];
;             kw4[qq] = ((const u32x2*)(zr + Z_KV))[lane];
;             const int pos = mm < MP ? (mm & (SEQ - 1)) : SEQ, l16 = lane & 15;
;             x1[qq] = bf2f(zr[Z_KR + l16]); x2[qq] = bf2f(zr[Z_KR + 16 + l16]); cs[qq] = cosT[pos * 16 + l16]; sn4[qq] = sinT[pos * 16 + l16]; }
; #pragma unroll
;         for (int qq = 0; qq < 4; ++qq) { const int m = m0 + qq * NGW; if (m >= MT) break;
;             float q[6]; float s = 0.f;
; #pragma unroll
;             for (int j = 0; j < 3; ++j) { const unsigned w = qw[qq][j]; q[2 * j] = bflo(w); q[2 * j + 1] = bfhi(w); s += q[2 * j] * q[2 * j] + q[2 * j + 1] * q[2 * j + 1]; }
;             const float rq = __builtin_amdgcn_rsqf(wave_sum(s) * (1.f / QL) + EPS);
; #pragma unroll
;             for (int j = 0; j < 3; ++j) { const f32x2 g = ((const f32x2*)qn)[lane + 64 * j]; ((unsigned*)((bf16*)(ws + WS_CQ) + (size_t)m * QL))[lane + 64 * j] = pk2(q[2 * j] * rq * g.x, q[2 * j + 1] * rq * g.y); }
;             const u32x2 kw = kw4[qq];
;             f32x4 kv = {bflo(kw.x), bfhi(kw.x), bflo(kw.y), bfhi(kw.y)};
;             const float rk = __builtin_amdgcn_rsqf(wave_sum((kv.x * kv.x + kv.y * kv.y) + (kv.z * kv.z + kv.w * kv.w)) * (1.f / KVL) + EPS);
;             kv = kv * rk * ((const f32x4*)kn)[lane];
.LBB0_871:
	s_add_i32 s47, s10, 0x4000
	s_cmpk_gt_i32 s47, 0x3fff
	s_cselect_b64 s[60:61], -1, 0
	s_and_b32 s44, s17, 0x1fff0
	s_cmpk_lt_i32 s47, 0x4000
	s_cselect_b32 s49, s44, 0x20000
	s_add_i32 s54, s68, s10
	s_add_i32 s45, s54, 0x4000
	s_cmpk_lt_i32 s45, 0x4100
	s_cselect_b64 s[58:59], -1, 0
	s_and_b64 s[50:51], s[58:59], exec
	s_cselect_b32 s44, s45, s47
	s_mul_i32 s48, s44, 0x2a00
	s_mul_hi_i32 s46, s44, 0x2a00
	s_add_u32 s50, s69, s48
	s_addc_u32 s51, s70, s46
	v_lshl_add_u64 v[0:1], s[50:51], 0, v[6:7]
	v_add_co_u32_e32 v0, vcc, s33, v0
	v_lshl_add_u64 v[42:43], s[8:9], 0, v[36:37]
	s_nop 0
	v_addc_co_u32_e32 v1, vcc, 0, v1, vcc
	v_lshl_add_u64 v[40:41], s[8:9], 0, v[34:35]
	v_add_co_u32_e32 v42, vcc, s5, v42
	s_add_u32 s62, s50, 0x1400
	s_nop 0
	v_addc_co_u32_e32 v43, vcc, 0, v43, vcc
	global_load_dwordx2 v[74:75], v[40:41], off
	global_load_dword v49, v[42:43], off offset:1536
	global_load_dword v50, v[42:43], off offset:1280
	global_load_dword v51, v[42:43], off offset:1024
	s_addc_u32 s63, s51, 0
	s_lshl_b32 s46, s44, 4
	s_and_b32 s46, s46, 0x1fff0
	s_cmpk_lt_i32 s44, 0x4000
	s_cselect_b32 s53, s46, 0x20000
	s_add_i32 s52, s71, s10
	s_add_i32 s48, s52, 0x4000
	s_cmpk_lt_i32 s48, 0x4100
	s_cselect_b64 s[56:57], -1, 0
	v_lshl_add_u64 v[2:3], s[50:51], 0, v[38:39]
	s_and_b64 s[50:51], s[56:57], exec
	s_cselect_b32 s44, s48, s47
	s_mul_i32 s50, s44, 0x2a00
	s_mul_hi_i32 s46, s44, 0x2a00
	s_add_u32 s50, s69, s50
	s_addc_u32 s51, s70, s46
	s_add_u32 s64, s50, 0x1400
	v_add_co_u32_e32 v2, vcc, s33, v2
	s_addc_u32 s65, s51, 0
	s_lshl_b32 s46, s44, 4
	v_addc_co_u32_e32 v3, vcc, 0, v3, vcc
	v_lshl_add_u64 v[40:41], s[50:51], 0, v[6:7]
	s_and_b32 s46, s46, 0x1fff0
	v_add_co_u32_e32 v40, vcc, s33, v40
	s_cmpk_lt_i32 s44, 0x4000
	s_nop 0
	v_addc_co_u32_e32 v41, vcc, 0, v41, vcc
	v_lshl_add_u64 v[42:43], s[50:51], 0, v[38:39]
	s_cselect_b32 s44, s46, 0x20000
	s_add_i32 s46, s72, s10
	v_add_co_u32_e32 v44, vcc, s33, v42
	v_or_b32_e32 v42, s44, v8
	s_add_i32 s44, s46, 0x4000
	s_cmpk_lt_i32 s44, 0x4100
	s_cselect_b64 s[50:51], -1, 0
	s_and_b64 s[66:67], s[50:51], exec
	s_cselect_b32 s55, s44, s47
	v_addc_co_u32_e32 v45, vcc, 0, v43, vcc
	v_lshlrev_b32_e32 v52, 2, v42
	global_load_dwordx2 v[70:71], v[14:15], off
	global_load_dwordx2 v[42:43], v[40:41], off offset:1792
	global_load_ushort v58, v[44:45], off offset:2304
	global_load_ushort v59, v[44:45], off offset:2336
	global_load_dword v57, v52, s[12:13]
	global_load_dword v56, v52, s[14:15]
	s_mul_i32 s66, s55, 0x2a00
	s_mul_hi_i32 s67, s55, 0x2a00
	s_add_u32 s66, s69, s66
	s_addc_u32 s67, s70, s67
	s_add_u32 s76, s66, 0x1400
	s_addc_u32 s77, s67, 0
	global_load_dword v68, v5, s[62:63]
	global_load_dword v67, v9, s[62:63]
	global_load_dword v60, v5, s[64:65]
	global_load_dword v53, v5, s[76:77]
	global_load_dword v69, v46, s[62:63]
	global_load_dwordx2 v[44:45], v[0:1], off offset:1792
	global_load_ushort v63, v[2:3], off offset:2304
	global_load_ushort v64, v[2:3], off offset:2336
	global_load_dword v62, v9, s[64:65]
	global_load_dword v61, v46, s[64:65]
	global_load_dword v54, v46, s[76:77]
	global_load_dword v55, v9, s[76:77]
	s_lshl_b32 s62, s55, 4
	s_and_b32 s62, s62, 0x1fff0
	s_cmpk_lt_i32 s55, 0x4000
	s_cselect_b32 s55, s62, 0x20000
	v_or_b32_e32 v40, s55, v8
	global_load_dwordx2 v[90:91], v[14:15], off
	global_load_dwordx2 v[92:93], v[14:15], off offset:512
	global_load_dwordx2 v[94:95], v[14:15], off offset:1024
	global_load_dwordx4 v[96:99], v[10:11], off
	s_waitcnt vmcnt(0)
	v_lshlrev_b32_e32 v65, 2, v40
	v_lshl_add_u64 v[0:1], s[66:67], 0, v[6:7]
	v_add_co_u32_e32 v0, vcc, s33, v0
	v_lshl_add_u64 v[2:3], s[66:67], 0, v[38:39]
	s_nop 0
	v_addc_co_u32_e32 v1, vcc, 0, v1, vcc
	v_add_co_u32_e32 v2, vcc, s33, v2
	s_mov_b64 s[64:65], -1
	s_nop 0
	v_addc_co_u32_e32 v3, vcc, 0, v3, vcc
	s_mov_b64 s[66:67], 0
	s_waitcnt vmcnt(0)
; __device__ __forceinline__ float bflo(unsigned w) { return __uint_as_float(w << 16); }
; __device__ __forceinline__ float bfhi(unsigned w) { return __uint_as_float(w & 0xffff0000u); }
; __device__ __forceinline__ unsigned pk2(float lo, float hi) { f32x2 v = {lo, hi}; bf16x2_t b = __builtin_convertvector(v, bf16x2_t); return __builtin_bit_cast(unsigned, b); }
; __device__ __forceinline__ void mla_prep(const Args& a, int vcu, int G, int lane, int wave) {
;     ...
;         for (int qq = 0; qq < 4; ++qq) { const int m = m0 + qq * NGW; if (m >= MT) break;
;             float q[6]; float s = 0.f;
; #pragma unroll
;             for (int j = 0; j < 3; ++j) { const unsigned w = qw[qq][j]; q[2 * j] = bflo(w); q[2 * j + 1] = bfhi(w); s += q[2 * j] * q[2 * j] + q[2 * j + 1] * q[2 * j + 1]; }
;             const float rq = __builtin_amdgcn_rsqf(wave_sum(s) * (1.f / QL) + EPS);
; #pragma unroll
;             for (int j = 0; j < 3; ++j) { const f32x2 g = ((const f32x2*)qn)[lane + 64 * j]; ((unsigned*)((bf16*)(ws + WS_CQ) + (size_t)m * QL))[lane + 64 * j] = pk2(q[2 * j] * rq * g.x, q[2 * j + 1] * rq * g.y); }
;             const u32x2 kw = kw4[qq];
;             f32x4 kv = {bflo(kw.x), bfhi(kw.x), bflo(kw.y), bfhi(kw.y)};
;             const float rk = __builtin_amdgcn_rsqf(wave_sum((kv.x * kv.x + kv.y * kv.y) + (kv.z * kv.z + kv.w * kv.w)) * (1.f / KVL) + EPS);
;             kv = kv * rk * ((const f32x4*)kn)[lane];
;             { u32x2 o; o.x = pk2(kv.x, kv.y); o.y = pk2(kv.z, kv.w); ((u32x2*)((bf16*)(ws + WS_CKV) + (size_t)m * KVL))[lane] = o; }
	v_lshlrev_b32_e32 v78, 16, v49
	v_lshlrev_b32_e32 v76, 16, v50
	v_lshlrev_b32_e32 v72, 16, v51
	v_and_b32_e32 v73, 0xffff0000, v51
	v_and_b32_e32 v77, 0xffff0000, v50
	v_and_b32_e32 v79, 0xffff0000, v49
	v_pk_mul_f32 v[40:41], v[72:73], v[72:73]
	v_pk_mul_f32 v[50:51], v[76:77], v[76:77]
	v_pk_mul_f32 v[80:81], v[78:79], v[78:79]
	v_add_f32_e32 v40, v40, v41
	v_add_f32_e32 v41, v50, v51
	v_add_f32_e32 v40, v41, v40
	v_add_f32_e32 v41, v80, v81
	v_add_f32_e32 v40, v41, v40
	s_nop 1
	v_add_f32_dpp v40, v40, v40 quad_perm:[1,0,3,2] row_mask:0xf bank_mask:0xf bound_ctrl:1
	s_nop 1
	v_add_f32_dpp v40, v40, v40 quad_perm:[2,3,0,1] row_mask:0xf bank_mask:0xf bound_ctrl:1
	s_nop 1
	v_add_f32_dpp v40, v40, v40 row_half_mirror row_mask:0xf bank_mask:0xf bound_ctrl:1
	s_nop 1
	v_add_f32_dpp v40, v40, v40 row_mirror row_mask:0xf bank_mask:0xf bound_ctrl:1
	v_mov_b32_e32 v41, v40
	s_nop 1
	v_permlane16_swap_b32_e32 v40, v41
	v_add_f32_e32 v40, v40, v41
	v_mov_b32_e32 v41, v40
	s_nop 1
	v_permlane32_swap_b32_e32 v40, v41
	v_add_f32_e32 v40, v40, v41
	v_fmamk_f32 v40, v40, 0x3b2aaaab, v47
	v_rsq_f32_e32 v66, v40
	global_load_dwordx2 v[40:41], v[0:1], off offset:1792
	global_load_ushort v51, v[2:3], off offset:2304
	global_load_ushort v52, v[2:3], off offset:2336
	global_load_dword v50, v65, s[12:13]
	global_load_dword v49, v65, s[14:15]
	v_lshl_add_u64 v[0:1], s[8:9], 0, v[30:31]
	v_add_co_u32_e32 v0, vcc, s74, v0
	v_or_b32_e32 v65, s49, v8
	s_nop 0
	v_addc_co_u32_e32 v1, vcc, 0, v1, vcc
	v_lshlrev_b32_e32 v65, 2, v65
	v_pk_mul_f32 v[2:3], v[66:67], v[72:73] op_sel_hi:[0,1]
	v_pk_mul_f32 v[2:3], v[70:71], v[2:3]
	v_pk_mul_f32 v[70:71], v[66:67], v[76:77] op_sel_hi:[0,1]
	v_cvt_pk_bf16_f32 v2, v2, v3
	global_store_dword v[0:1], v2, off
	s_nop 0
	v_mov_b64_e32 v[2:3], v[92:93]
	v_pk_mul_f32 v[72:73], v[66:67], v[78:79] op_sel_hi:[0,1]
	v_lshlrev_b32_e32 v78, 16, v74
	v_and_b32_e32 v79, 0xffff0000, v74
	v_lshlrev_b32_e32 v74, 16, v75
	v_and_b32_e32 v75, 0xffff0000, v75
	v_mul_f32_e32 v80, v79, v79
	v_mul_f32_e32 v81, v75, v75
	v_fmac_f32_e32 v80, v78, v78
	v_fmac_f32_e32 v81, v74, v74
	v_add_f32_e32 v80, v80, v81
	v_lshl_add_u64 v[76:77], s[8:9], 0, v[28:29]
	v_pk_mul_f32 v[2:3], v[2:3], v[70:71]
	s_nop 0
	v_cvt_pk_bf16_f32 v2, v2, v3
	global_store_dword v[0:1], v2, off offset:256
	s_nop 0
	v_mov_b64_e32 v[2:3], v[94:95]
	v_lshl_add_u64 v[70:71], s[8:9], 0, v[32:33]
	v_add_co_u32_e32 v70, vcc, s5, v70
	v_add_f32_dpp v80, v80, v80 quad_perm:[1,0,3,2] row_mask:0xf bank_mask:0xf bound_ctrl:1
	s_nop 0
	v_addc_co_u32_e32 v71, vcc, 0, v71, vcc
	v_add_f32_dpp v80, v80, v80 quad_perm:[2,3,0,1] row_mask:0xf bank_mask:0xf bound_ctrl:1
	s_and_b64 vcc, exec, s[60:61]
	v_pk_mul_f32 v[2:3], v[2:3], v[72:73]
	s_nop 0
	v_cvt_pk_bf16_f32 v2, v2, v3
	global_store_dword v[0:1], v2, off offset:512
	s_nop 0
	v_mov_b64_e32 v[0:1], v[96:97]
	v_mov_b64_e32 v[2:3], v[98:99]
	s_nop 0
	global_load_ushort v72, v[70:71], off offset:2304
	global_load_ushort v73, v[70:71], off offset:2336
	s_nop 0
	global_load_dword v71, v65, s[12:13]
	global_load_dword v70, v65, s[14:15]
	v_or_b32_e32 v65, s53, v8
	v_lshlrev_b32_e32 v65, 2, v65
	global_load_dword v66, v65, s[12:13]
	s_nop 0
	global_load_dword v65, v65, s[14:15]
	v_add_f32_dpp v80, v80, v80 row_half_mirror row_mask:0xf bank_mask:0xf bound_ctrl:1
	s_nop 1
	v_add_f32_dpp v80, v80, v80 row_mirror row_mask:0xf bank_mask:0xf bound_ctrl:1
	v_mov_b32_e32 v81, v80
	s_nop 1
	v_permlane16_swap_b32_e32 v80, v81
	v_add_f32_e32 v80, v80, v81
	v_mov_b32_e32 v81, v80
	s_nop 1
	v_permlane32_swap_b32_e32 v80, v81
	v_add_f32_e32 v80, v80, v81
	v_fmamk_f32 v80, v80, 0x3b800000, v47
	v_rsq_f32_e32 v80, v80
	s_nop 0
	v_pk_mul_f32 v[74:75], v[74:75], v[80:81] op_sel_hi:[1,0]
	v_pk_mul_f32 v[78:79], v[78:79], v[80:81] op_sel_hi:[1,0]
	v_pk_mul_f32 v[2:3], v[2:3], v[74:75]
	v_pk_mul_f32 v[0:1], v[0:1], v[78:79]
	v_cvt_pk_bf16_f32 v75, v2, v3
	v_cvt_pk_bf16_f32 v74, v0, v1
	global_store_dwordx2 v[76:77], v[74:75], off
	s_cbranch_vccz .LBB0_874
	s_mov_b64 s[64:65], 0
	s_cmpk_lt_u32 s47, 0x4080
	s_cbranch_scc0 .LBB0_874
	s_load_dwordx2 s[62:63], s[6:7], 0x148
	s_lshl_b64 s[66:67], s[10:11], 10
	s_waitcnt lgkmcnt(0)
	s_add_u32 s49, s62, s66
	s_addc_u32 s53, s63, s67
	s_add_u32 s62, s49, 0x528a000
	s_addc_u32 s63, s53, 0
	s_mov_b64 s[66:67], -1

; __device__ __forceinline__ float bflo(unsigned w) { return __uint_as_float(w << 16); }
; __device__ __forceinline__ float bfhi(unsigned w) { return __uint_as_float(w & 0xffff0000u); }
; __device__ __forceinline__ unsigned pk2(float lo, float hi) { f32x2 v = {lo, hi}; bf16x2_t b = __builtin_convertvector(v, bf16x2_t); return __builtin_bit_cast(unsigned, b); }
; __device__ __forceinline__ void mla_prep(const Args& a, int vcu, int G, int lane, int wave) {
;     ...
;         for (int qq = 0; qq < 4; ++qq) { const int m = m0 + qq * NGW; if (m >= MT) break;
;             float q[6]; float s = 0.f;
; #pragma unroll
;             for (int j = 0; j < 3; ++j) { const unsigned w = qw[qq][j]; q[2 * j] = bflo(w); q[2 * j + 1] = bfhi(w); s += q[2 * j] * q[2 * j] + q[2 * j + 1] * q[2 * j + 1]; }
;             const float rq = __builtin_amdgcn_rsqf(wave_sum(s) * (1.f / QL) + EPS);
; #pragma unroll
;             for (int j = 0; j < 3; ++j) { const f32x2 g = ((const f32x2*)qn)[lane + 64 * j]; ((unsigned*)((bf16*)(ws + WS_CQ) + (size_t)m * QL))[lane + 64 * j] = pk2(q[2 * j] * rq * g.x, q[2 * j + 1] * rq * g.y); }
;             const u32x2 kw = kw4[qq];
;             f32x4 kv = {bflo(kw.x), bfhi(kw.x), bflo(kw.y), bfhi(kw.y)};
;             const float rk = __builtin_amdgcn_rsqf(wave_sum((kv.x * kv.x + kv.y * kv.y) + (kv.z * kv.z + kv.w * kv.w)) * (1.f / KVL) + EPS);
;             kv = kv * rk * ((const f32x4*)kn)[lane];
;             { u32x2 o; o.x = pk2(kv.x, kv.y); o.y = pk2(kv.z, kv.w); ((u32x2*)((bf16*)(ws + WS_CKV) + (size_t)m * KVL))[lane] = o; }
.LBB0_886:
	s_or_b64 exec, exec, s[62:63]
	s_andn2_b64 vcc, exec, s[58:59]
	s_cbranch_vccnz .LBB0_870
	v_mov_b64_e32 v[0:1], v[90:91]
	v_lshlrev_b32_e32 v2, 16, v68
	v_and_b32_e32 v3, 0xffff0000, v68
	s_waitcnt vmcnt(3)
	v_lshlrev_b32_e32 v70, 16, v67
	v_and_b32_e32 v71, 0xffff0000, v67
	v_lshlrev_b32_e32 v68, 16, v69
	v_and_b32_e32 v69, 0xffff0000, v69
	v_pk_mul_f32 v[74:75], v[2:3], v[2:3]
	v_pk_mul_f32 v[76:77], v[70:71], v[70:71]
	v_pk_mul_f32 v[78:79], v[68:69], v[68:69]
	v_add_f32_e32 v67, v76, v77
	v_add_f32_e32 v74, v74, v75
	v_add_f32_e32 v75, v78, v79
	v_add_f32_e32 v67, v74, v67
	v_add_f32_e32 v67, v67, v75
	v_lshl_add_u64 v[72:73], s[8:9], 0, v[24:25]
	v_add_co_u32_e32 v72, vcc, s74, v72
	v_add_f32_dpp v67, v67, v67 quad_perm:[1,0,3,2] row_mask:0xf bank_mask:0xf bound_ctrl:1
	s_nop 0
	v_addc_co_u32_e32 v73, vcc, 0, v73, vcc
	v_add_f32_dpp v67, v67, v67 quad_perm:[2,3,0,1] row_mask:0xf bank_mask:0xf bound_ctrl:1
	s_cmpk_gt_i32 s45, 0x3fff
	s_cselect_b64 s[58:59], -1, 0
	v_add_f32_dpp v67, v67, v67 row_half_mirror row_mask:0xf bank_mask:0xf bound_ctrl:1
	s_cmpk_lt_i32 s45, 0x4000
	s_nop 0
	v_add_f32_dpp v67, v67, v67 row_mirror row_mask:0xf bank_mask:0xf bound_ctrl:1
	v_mov_b32_e32 v74, v67
	s_nop 1
	v_permlane16_swap_b32_e32 v67, v74
	v_add_f32_e32 v67, v67, v74
	v_mov_b32_e32 v74, v67
	s_nop 1
	v_permlane32_swap_b32_e32 v67, v74
	v_add_f32_e32 v67, v67, v74
	v_fmamk_f32 v67, v67, 0x3b2aaaab, v47
	v_rsq_f32_e32 v74, v67
	s_nop 0
	v_pk_mul_f32 v[2:3], v[74:75], v[2:3] op_sel_hi:[0,1]
	v_pk_mul_f32 v[0:1], v[0:1], v[2:3]
	s_nop 0
	v_cvt_pk_bf16_f32 v0, v0, v1
	global_store_dword v[72:73], v0, off
	s_nop 0
	v_mov_b64_e32 v[0:1], v[92:93]
	v_pk_mul_f32 v[2:3], v[74:75], v[70:71] op_sel_hi:[0,1]
	v_pk_mul_f32 v[0:1], v[0:1], v[2:3]
	s_nop 0
	v_cvt_pk_bf16_f32 v0, v0, v1
	global_store_dword v[72:73], v0, off offset:256
	s_nop 0
	v_mov_b64_e32 v[0:1], v[94:95]
	v_pk_mul_f32 v[2:3], v[74:75], v[68:69] op_sel_hi:[0,1]
	v_lshlrev_b32_e32 v68, 16, v44
	v_and_b32_e32 v69, 0xffff0000, v44
	v_lshlrev_b32_e32 v44, 16, v45
	v_and_b32_e32 v45, 0xffff0000, v45
	v_mul_f32_e32 v67, v69, v69
	v_mul_f32_e32 v70, v45, v45
	v_fmac_f32_e32 v67, v68, v68
	v_fmac_f32_e32 v70, v44, v44
	v_add_f32_e32 v67, v67, v70
	v_pk_mul_f32 v[0:1], v[0:1], v[2:3]
	s_nop 0
	v_cvt_pk_bf16_f32 v0, v0, v1
	global_store_dword v[72:73], v0, off offset:512
	s_nop 0
	v_mov_b64_e32 v[0:1], v[96:97]
	v_mov_b64_e32 v[2:3], v[98:99]
	v_add_f32_dpp v67, v67, v67 quad_perm:[1,0,3,2] row_mask:0xf bank_mask:0xf bound_ctrl:1
	v_lshl_add_u64 v[72:73], s[8:9], 0, v[22:23]
	s_nop 0
	v_add_f32_dpp v67, v67, v67 quad_perm:[2,3,0,1] row_mask:0xf bank_mask:0xf bound_ctrl:1
	s_nop 1
	v_add_f32_dpp v67, v67, v67 row_half_mirror row_mask:0xf bank_mask:0xf bound_ctrl:1
	s_nop 1
	v_add_f32_dpp v67, v67, v67 row_mirror row_mask:0xf bank_mask:0xf bound_ctrl:1
	v_mov_b32_e32 v70, v67
	s_nop 1
	v_permlane16_swap_b32_e32 v67, v70
	v_add_f32_e32 v67, v67, v70
	v_mov_b32_e32 v70, v67
	s_nop 1
	v_permlane32_swap_b32_e32 v67, v70
	v_add_f32_e32 v67, v67, v70
	v_fmamk_f32 v67, v67, 0x3b800000, v47
	v_rsq_f32_e32 v70, v67
	s_nop 0
	v_pk_mul_f32 v[44:45], v[44:45], v[70:71] op_sel_hi:[1,0]
	v_pk_mul_f32 v[68:69], v[68:69], v[70:71] op_sel_hi:[1,0]
	s_waitcnt vmcnt(3)
	v_pk_mul_f32 v[2:3], v[2:3], v[44:45]
	v_pk_mul_f32 v[0:1], v[0:1], v[68:69]
	v_cvt_pk_bf16_f32 v45, v2, v3
	v_cvt_pk_bf16_f32 v44, v0, v1
	global_store_dwordx2 v[72:73], v[44:45], off
	s_cbranch_scc1 .LBB0_890
	s_mov_b64 s[62:63], 0
	s_cmpk_lt_u32 s45, 0x4080
	s_mov_b64 s[64:65], 0
	s_cbranch_scc0 .LBB0_891
	s_load_dwordx2 s[60:61], s[6:7], 0x148
	s_mov_b32 s55, s11
	s_lshl_b64 s[64:65], s[54:55], 10
	s_waitcnt lgkmcnt(0)
	s_add_u32 s47, s60, s64
	s_addc_u32 s49, s61, s65
	s_add_u32 s60, s47, 0x528a000
	s_addc_u32 s61, s49, 0
	s_mov_b64 s[64:65], -1
	s_branch .LBB0_891

; __device__ __forceinline__ float bflo(unsigned w) { return __uint_as_float(w << 16); }
; __device__ __forceinline__ float bfhi(unsigned w) { return __uint_as_float(w & 0xffff0000u); }
; __device__ __forceinline__ unsigned pk2(float lo, float hi) { f32x2 v = {lo, hi}; bf16x2_t b = __builtin_convertvector(v, bf16x2_t); return __builtin_bit_cast(unsigned, b); }
; __device__ __forceinline__ void mla_prep(const Args& a, int vcu, int G, int lane, int wave) {
;     ...
;         for (int qq = 0; qq < 4; ++qq) { const int m = m0 + qq * NGW; if (m >= MT) break;
;             float q[6]; float s = 0.f;
; #pragma unroll
;             for (int j = 0; j < 3; ++j) { const unsigned w = qw[qq][j]; q[2 * j] = bflo(w); q[2 * j + 1] = bfhi(w); s += q[2 * j] * q[2 * j] + q[2 * j + 1] * q[2 * j + 1]; }
;             const float rq = __builtin_amdgcn_rsqf(wave_sum(s) * (1.f / QL) + EPS);
; #pragma unroll
;             for (int j = 0; j < 3; ++j) { const f32x2 g = ((const f32x2*)qn)[lane + 64 * j]; ((unsigned*)((bf16*)(ws + WS_CQ) + (size_t)m * QL))[lane + 64 * j] = pk2(q[2 * j] * rq * g.x, q[2 * j + 1] * rq * g.y); }
;             const u32x2 kw = kw4[qq];
;             f32x4 kv = {bflo(kw.x), bfhi(kw.x), bflo(kw.y), bfhi(kw.y)};
;             const float rk = __builtin_amdgcn_rsqf(wave_sum((kv.x * kv.x + kv.y * kv.y) + (kv.z * kv.z + kv.w * kv.w)) * (1.f / KVL) + EPS);
;             kv = kv * rk * ((const f32x4*)kn)[lane];
;             { u32x2 o; o.x = pk2(kv.x, kv.y); o.y = pk2(kv.z, kv.w); ((u32x2*)((bf16*)(ws + WS_CKV) + (size_t)m * KVL))[lane] = o; }
.LBB0_903:
	s_or_b64 exec, exec, s[60:61]
	s_andn2_b64 vcc, exec, s[56:57]
	s_cbranch_vccnz .LBB0_870
	v_mov_b64_e32 v[0:1], v[90:91]
	v_lshlrev_b32_e32 v2, 16, v60
	v_and_b32_e32 v3, 0xffff0000, v60
	v_lshlrev_b32_e32 v44, 16, v62
	v_and_b32_e32 v45, 0xffff0000, v62
	v_lshlrev_b32_e32 v60, 16, v61
	v_and_b32_e32 v61, 0xffff0000, v61
	v_pk_mul_f32 v[62:63], v[2:3], v[2:3]
	v_pk_mul_f32 v[64:65], v[44:45], v[44:45]
	v_pk_mul_f32 v[66:67], v[60:61], v[60:61]
	v_add_f32_e32 v64, v64, v65
	v_add_f32_e32 v62, v62, v63
	v_add_f32_e32 v63, v66, v67
	v_add_f32_e32 v62, v62, v64
	v_add_f32_e32 v62, v62, v63
	v_mad_i64_i32 v[64:65], s[54:55], s48, v48, v[16:17]
	s_nop 0
	v_add_f32_dpp v62, v62, v62 quad_perm:[1,0,3,2] row_mask:0xf bank_mask:0xf bound_ctrl:1
	s_ashr_i32 s49, s48, 31
	s_lshl_b64 s[54:55], s[48:49], 9
	v_add_f32_dpp v62, v62, v62 quad_perm:[2,3,0,1] row_mask:0xf bank_mask:0xf bound_ctrl:1
	s_cmpk_gt_i32 s48, 0x3fff
	s_nop 0
	v_add_f32_dpp v62, v62, v62 row_half_mirror row_mask:0xf bank_mask:0xf bound_ctrl:1
	s_nop 1
	v_add_f32_dpp v62, v62, v62 row_mirror row_mask:0xf bank_mask:0xf bound_ctrl:1
	v_mov_b32_e32 v63, v62
	s_nop 1
	v_permlane16_swap_b32_e32 v62, v63
	v_add_f32_e32 v62, v62, v63
	v_mov_b32_e32 v63, v62
	s_nop 1
	v_permlane32_swap_b32_e32 v62, v63
	v_add_f32_e32 v62, v62, v63
	v_fmamk_f32 v62, v62, 0x3b2aaaab, v47
	v_rsq_f32_e32 v62, v62
	s_nop 0
	v_pk_mul_f32 v[2:3], v[62:63], v[2:3] op_sel_hi:[0,1]
	v_pk_mul_f32 v[0:1], v[0:1], v[2:3]
	s_nop 0
	v_cvt_pk_bf16_f32 v0, v0, v1
	global_store_dword v[64:65], v0, off
	s_nop 0
	v_mov_b64_e32 v[0:1], v[92:93]
	v_pk_mul_f32 v[2:3], v[62:63], v[44:45] op_sel_hi:[0,1]
	v_lshlrev_b32_e32 v44, 16, v42
	v_and_b32_e32 v45, 0xffff0000, v42
	v_lshlrev_b32_e32 v42, 16, v43
	v_and_b32_e32 v43, 0xffff0000, v43
	v_pk_mul_f32 v[0:1], v[0:1], v[2:3]
	s_nop 0
	v_cvt_pk_bf16_f32 v0, v0, v1
	global_store_dword v[64:65], v0, off offset:256
	s_nop 0
	v_mov_b64_e32 v[0:1], v[94:95]
	v_pk_mul_f32 v[2:3], v[62:63], v[60:61] op_sel_hi:[0,1]
	v_mul_f32_e32 v60, v45, v45
	v_mul_f32_e32 v61, v43, v43
	v_fmac_f32_e32 v60, v44, v44
	v_fmac_f32_e32 v61, v42, v42
	v_add_f32_e32 v60, v60, v61
	v_lshl_add_u64 v[62:63], v[12:13], 0, s[54:55]
	s_cselect_b64 s[54:55], -1, 0
	v_add_f32_dpp v60, v60, v60 quad_perm:[1,0,3,2] row_mask:0xf bank_mask:0xf bound_ctrl:1
	s_cmpk_lt_i32 s48, 0x4000
	v_pk_mul_f32 v[0:1], v[0:1], v[2:3]
	s_nop 0
	v_cvt_pk_bf16_f32 v0, v0, v1
	global_store_dword v[64:65], v0, off offset:512
	s_nop 0
	v_mov_b64_e32 v[0:1], v[96:97]
	v_mov_b64_e32 v[2:3], v[98:99]
	v_add_f32_dpp v60, v60, v60 quad_perm:[2,3,0,1] row_mask:0xf bank_mask:0xf bound_ctrl:1
	s_nop 1
	v_add_f32_dpp v60, v60, v60 row_half_mirror row_mask:0xf bank_mask:0xf bound_ctrl:1
	s_nop 1
	v_add_f32_dpp v60, v60, v60 row_mirror row_mask:0xf bank_mask:0xf bound_ctrl:1
	v_mov_b32_e32 v61, v60
	s_nop 1
	v_permlane16_swap_b32_e32 v60, v61
	v_add_f32_e32 v60, v60, v61
	v_mov_b32_e32 v61, v60
	s_nop 1
	v_permlane32_swap_b32_e32 v60, v61
	v_add_f32_e32 v60, v60, v61
	v_fmamk_f32 v60, v60, 0x3b800000, v47
	v_rsq_f32_e32 v60, v60
	s_nop 0
	v_pk_mul_f32 v[42:43], v[42:43], v[60:61] op_sel_hi:[1,0]
	v_pk_mul_f32 v[44:45], v[44:45], v[60:61] op_sel_hi:[1,0]
	s_waitcnt vmcnt(3)
	v_pk_mul_f32 v[2:3], v[2:3], v[42:43]
	v_pk_mul_f32 v[0:1], v[0:1], v[44:45]
	v_cvt_pk_bf16_f32 v43, v2, v3
	v_cvt_pk_bf16_f32 v42, v0, v1
	global_store_dwordx2 v[62:63], v[42:43], off
	s_cbranch_scc1 .LBB0_907
	s_mov_b64 s[58:59], 0
	s_cmpk_lt_u32 s48, 0x4080
	s_mov_b64 s[60:61], 0
	s_cbranch_scc0 .LBB0_908
	s_load_dwordx2 s[56:57], s[6:7], 0x148
	s_mov_b32 s53, s11
	s_lshl_b64 s[60:61], s[52:53], 10
	s_waitcnt lgkmcnt(0)
	s_add_u32 s45, s56, s60
	s_addc_u32 s47, s57, s61
	s_add_u32 s56, s45, 0x528a000
	s_addc_u32 s57, s47, 0
	s_mov_b64 s[60:61], -1
	s_branch .LBB0_908

; __device__ __forceinline__ float bflo(unsigned w) { return __uint_as_float(w << 16); }
; __device__ __forceinline__ float bfhi(unsigned w) { return __uint_as_float(w & 0xffff0000u); }
; __device__ __forceinline__ unsigned pk2(float lo, float hi) { f32x2 v = {lo, hi}; bf16x2_t b = __builtin_convertvector(v, bf16x2_t); return __builtin_bit_cast(unsigned, b); }
; __device__ __forceinline__ void mla_prep(const Args& a, int vcu, int G, int lane, int wave) {
;     ...
;         for (int qq = 0; qq < 4; ++qq) { const int m = m0 + qq * NGW; if (m >= MT) break;
;             float q[6]; float s = 0.f;
; #pragma unroll
;             for (int j = 0; j < 3; ++j) { const unsigned w = qw[qq][j]; q[2 * j] = bflo(w); q[2 * j + 1] = bfhi(w); s += q[2 * j] * q[2 * j] + q[2 * j + 1] * q[2 * j + 1]; }
;             const float rq = __builtin_amdgcn_rsqf(wave_sum(s) * (1.f / QL) + EPS);
; #pragma unroll
;             for (int j = 0; j < 3; ++j) { const f32x2 g = ((const f32x2*)qn)[lane + 64 * j]; ((unsigned*)((bf16*)(ws + WS_CQ) + (size_t)m * QL))[lane + 64 * j] = pk2(q[2 * j] * rq * g.x, q[2 * j + 1] * rq * g.y); }
;             const u32x2 kw = kw4[qq];
;             f32x4 kv = {bflo(kw.x), bfhi(kw.x), bflo(kw.y), bfhi(kw.y)};
;             const float rk = __builtin_amdgcn_rsqf(wave_sum((kv.x * kv.x + kv.y * kv.y) + (kv.z * kv.z + kv.w * kv.w)) * (1.f / KVL) + EPS);
;             kv = kv * rk * ((const f32x4*)kn)[lane];
;             { u32x2 o; o.x = pk2(kv.x, kv.y); o.y = pk2(kv.z, kv.w); ((u32x2*)((bf16*)(ws + WS_CKV) + (size_t)m * KVL))[lane] = o; }
.LBB0_920:
	s_or_b64 exec, exec, s[56:57]
	s_andn2_b64 vcc, exec, s[50:51]
	s_cbranch_vccnz .LBB0_870
	v_mov_b64_e32 v[0:1], v[90:91]
	v_lshlrev_b32_e32 v2, 16, v53
	v_and_b32_e32 v3, 0xffff0000, v53
	v_lshlrev_b32_e32 v42, 16, v55
	v_and_b32_e32 v43, 0xffff0000, v55
	v_lshlrev_b32_e32 v44, 16, v54
	v_and_b32_e32 v45, 0xffff0000, v54
	v_pk_mul_f32 v[54:55], v[2:3], v[2:3]
	v_pk_mul_f32 v[56:57], v[42:43], v[42:43]
	v_pk_mul_f32 v[58:59], v[44:45], v[44:45]
	v_add_f32_e32 v53, v56, v57
	v_add_f32_e32 v54, v54, v55
	v_add_f32_e32 v55, v58, v59
	v_add_f32_e32 v53, v54, v53
	v_add_f32_e32 v53, v53, v55
	v_mad_i64_i32 v[56:57], s[48:49], s44, v48, v[16:17]
	s_nop 0
	v_add_f32_dpp v53, v53, v53 quad_perm:[1,0,3,2] row_mask:0xf bank_mask:0xf bound_ctrl:1
	s_ashr_i32 s45, s44, 31
	s_lshl_b64 s[48:49], s[44:45], 9
	v_add_f32_dpp v53, v53, v53 quad_perm:[2,3,0,1] row_mask:0xf bank_mask:0xf bound_ctrl:1
	s_cmpk_gt_i32 s44, 0x3fff
	s_nop 0
	v_add_f32_dpp v53, v53, v53 row_half_mirror row_mask:0xf bank_mask:0xf bound_ctrl:1
	s_nop 1
	v_add_f32_dpp v53, v53, v53 row_mirror row_mask:0xf bank_mask:0xf bound_ctrl:1
	v_mov_b32_e32 v54, v53
	s_nop 1
	v_permlane16_swap_b32_e32 v53, v54
	v_add_f32_e32 v53, v53, v54
	v_mov_b32_e32 v54, v53
	s_nop 1
	v_permlane32_swap_b32_e32 v53, v54
	v_add_f32_e32 v53, v53, v54
	v_fmamk_f32 v53, v53, 0x3b2aaaab, v47
	v_rsq_f32_e32 v54, v53
	s_nop 0
	v_pk_mul_f32 v[2:3], v[54:55], v[2:3] op_sel_hi:[0,1]
	v_pk_mul_f32 v[0:1], v[0:1], v[2:3]
	s_nop 0
	v_cvt_pk_bf16_f32 v0, v0, v1
	global_store_dword v[56:57], v0, off
	s_nop 0
	v_mov_b64_e32 v[0:1], v[92:93]
	v_pk_mul_f32 v[2:3], v[54:55], v[42:43] op_sel_hi:[0,1]
	v_lshlrev_b32_e32 v42, 16, v40
	v_and_b32_e32 v43, 0xffff0000, v40
	v_lshlrev_b32_e32 v40, 16, v41
	v_and_b32_e32 v41, 0xffff0000, v41
	v_pk_mul_f32 v[0:1], v[0:1], v[2:3]
	s_nop 0
	v_cvt_pk_bf16_f32 v0, v0, v1
	global_store_dword v[56:57], v0, off offset:256
	s_nop 0
	v_mov_b64_e32 v[0:1], v[94:95]
	v_pk_mul_f32 v[2:3], v[54:55], v[44:45] op_sel_hi:[0,1]
	v_mul_f32_e32 v44, v43, v43
	v_mul_f32_e32 v45, v41, v41
	v_fmac_f32_e32 v44, v42, v42
	v_fmac_f32_e32 v45, v40, v40
	v_add_f32_e32 v44, v44, v45
	v_lshl_add_u64 v[54:55], v[12:13], 0, s[48:49]
	s_cselect_b64 s[48:49], -1, 0
	v_add_f32_dpp v44, v44, v44 quad_perm:[1,0,3,2] row_mask:0xf bank_mask:0xf bound_ctrl:1
	s_cmpk_lt_i32 s44, 0x4000
	v_pk_mul_f32 v[0:1], v[0:1], v[2:3]
	s_nop 0
	v_cvt_pk_bf16_f32 v0, v0, v1
	global_store_dword v[56:57], v0, off offset:512
	s_nop 0
	v_mov_b64_e32 v[0:1], v[96:97]
	v_mov_b64_e32 v[2:3], v[98:99]
	v_add_f32_dpp v44, v44, v44 quad_perm:[2,3,0,1] row_mask:0xf bank_mask:0xf bound_ctrl:1
	s_nop 1
	v_add_f32_dpp v44, v44, v44 row_half_mirror row_mask:0xf bank_mask:0xf bound_ctrl:1
	s_nop 1
	v_add_f32_dpp v44, v44, v44 row_mirror row_mask:0xf bank_mask:0xf bound_ctrl:1
	v_mov_b32_e32 v45, v44
	s_nop 1
	v_permlane16_swap_b32_e32 v44, v45
	v_add_f32_e32 v44, v44, v45
	v_mov_b32_e32 v45, v44
	s_nop 1
	v_permlane32_swap_b32_e32 v44, v45
	v_add_f32_e32 v44, v44, v45
	v_fmamk_f32 v44, v44, 0x3b800000, v47
	v_rsq_f32_e32 v44, v44
	s_nop 0
	v_pk_mul_f32 v[40:41], v[40:41], v[44:45] op_sel_hi:[1,0]
	v_pk_mul_f32 v[42:43], v[42:43], v[44:45] op_sel_hi:[1,0]
	s_waitcnt vmcnt(3)
	v_pk_mul_f32 v[2:3], v[2:3], v[40:41]
	v_pk_mul_f32 v[0:1], v[0:1], v[42:43]
	v_cvt_pk_bf16_f32 v41, v2, v3
	v_cvt_pk_bf16_f32 v40, v0, v1
	global_store_dwordx2 v[54:55], v[40:41], off
	s_cbranch_scc1 .LBB0_924
	s_mov_b64 s[52:53], 0
	s_cmpk_lt_u32 s44, 0x4080
	s_mov_b64 s[54:55], 0
	s_cbranch_scc0 .LBB0_925
	s_load_dwordx2 s[50:51], s[6:7], 0x148
	s_mov_b32 s47, s11
	s_lshl_b64 s[54:55], s[46:47], 10
	s_waitcnt lgkmcnt(0)
	s_add_u32 s47, s50, s54
	s_addc_u32 s51, s51, s55
	s_add_u32 s50, s47, 0x528a000
	s_addc_u32 s51, s51, 0
	s_mov_b64 s[54:55], -1
	s_branch .LBB0_925

; #define SBAR() __builtin_amdgcn_sched_barrier(0)
; #define DMA_K(t, slot) do { if constexpr ((VAR & 16) != 0) break; __builtin_amdgcn_global_load_lds((const unsigned*)(ksrc + (size_t)TT(t) * 64 * KVW), (LAS unsigned*)(kdst + (slot) * KSLOT), 16, 0, 0); \
;                             __builtin_amdgcn_global_load_lds((const unsigned*)(rsrc + (size_t)TT(t) * 64 * ROPE), (LAS unsigned*)(rdst + (slot) * KSLOT), 16, 0, 0); } while (0)
; #define DMA_V(t, slot) do { if constexpr ((VAR & 16) == 0) __builtin_amdgcn_global_load_lds((const unsigned*)(vsrc + (size_t)TT(t) * 64 * KVW), (LAS unsigned*)(vdst + (slot) * VSLOT), 16, 0, 0); } while (0)
; #define KLOAD(slot) do { const LAS unsigned char* kb_ = kb0 + (slot) * KSLOT; _Pragma("unroll") for (int d0 = 0; d0 < 6; ++d0) { kf[2 * d0] = *(const LAS bf16x8*)(kb_ + d0 * 512); kf[2 * d0 + 1] = *(const LAS bf16x8*)(kb_ + d0 * 512 + 6144); } } while (0)
; #define VREAD(slot) do { const int vb_ = vb0 + (slot) * VSLOT; \
;         TRRD(vl[0], 0); TRRD(vh[0], 512); TRRD(vl[1], 1024); TRRD(vh[1], 1536); TRRD(vl[2], 2048); TRRD(vh[2], 2560); TRRD(vl[3], 3072); TRRD(vh[3], 3584); \
;         TRRD(vl[4], 4096); TRRD(vh[4], 4608); TRRD(vl[5], 5120); TRRD(vh[5], 5632); TRRD(vl[6], 6144); TRRD(vh[6], 6656); TRRD(vl[7], 7168); TRRD(vh[7], 7680); } while (0)
; template <int VAR> __device__ __forceinline__ void block(const bf16* Q, const bf16* KVB, const bf16* KR, const float* cosT, bf16* OB, LAS unsigned char* lds, int b, int h, int qb, int t0, int wv, ...
;     ...
;         { if (t + 3 < NT) DMA_K(t + 3, (sk + 3) & 3); if (t + 2 < NT) DMA_V(t + 2, (sk + 2) & 3); }
;         SBAR();
;         KLOAD(sk); VREAD(sv);
;         SBAR();
;         QK(px0, px1);
.Lat_mreads:
	s_setprio 1
	s_mul_i32 s98, s82, 0x3000
	v_add_u32_e32 v218, s98, v149
	v_lshl_add_u32 v255, s68, 13, v172
	ds_read_b128 v[48:51], v218
	ds_read_b128 v[174:177], v218 offset:512
	ds_read_b128 v[178:181], v218 offset:6144
	ds_read_b128 v[182:185], v218 offset:6656
	ds_read_b128 v[186:189], v218 offset:1024
	ds_read_b128 v[194:197], v218 offset:7168
	ds_read_b128 v[190:193], v218 offset:1536
	ds_read_b128 v[198:201], v218 offset:7680
	ds_read_b128 v[202:205], v218 offset:2048
	ds_read_b128 v[210:213], v218 offset:8192
	ds_read_b128 v[206:209], v218 offset:2560
	ds_read_b128 v[214:217], v218 offset:8704
	ds_read_b64_tr_b16 v[220:221], v255 offset:0x0
	ds_read_b64_tr_b16 v[222:223], v255 offset:0x200
	ds_read_b64_tr_b16 v[226:227], v255 offset:0x400
	s_waitcnt lgkmcnt(14)
	v_mfma_f32_32x32x16_bf16 v[64:79], v[48:51], v[112:115], v[32:47]
	ds_read_b64_tr_b16 v[228:229], v255 offset:0x600
	s_waitcnt lgkmcnt(14)
	v_mfma_f32_32x32x16_bf16 v[64:79], v[174:177], v[104:107], v[64:79]
	ds_read_b64_tr_b16 v[230:231], v255 offset:0x800
	s_waitcnt lgkmcnt(14)
	v_mfma_f32_32x32x16_bf16 v[48:63], v[178:181], v[112:115], v[32:47]
	ds_read_b64_tr_b16 v[232:233], v255 offset:0xa00
	s_waitcnt lgkmcnt(14)
	v_mfma_f32_32x32x16_bf16 v[48:63], v[182:185], v[104:107], v[48:63]
	s_cmp_lt_u32 s85, s66
	s_cbranch_scc0 .Lat_nodmak
	s_add_i32 s98, s82, -1
	s_and_b32 s98, s98, 3
	s_mulk_i32 s98, 0x3000
	s_add_i32 m0, s1, s98
	s_add_i32 s98, s0, s98
	global_load_lds_dwordx4 v[158:159], off
	s_add_i32 m0, s98, 0x800
	s_nop 0
	global_load_lds_dwordx4 v[156:157], off

; #define SHIFT(P0_, P1_, dl_) do { m_reg += (dl_); _Pragma("unroll") for (int r = 0; r < 16; ++r) { P0_[r] -= (dl_); P1_[r] -= (dl_); } _Pragma("unroll") for (int r = 0; r < 16; ++r) negm[r] = -m_reg; } while (0)
; template <int VAR> __device__ __forceinline__ void block(const bf16* Q, const bf16* KVB, const bf16* KR, const float* cosT, bf16* OB, LAS unsigned char* lds, int b, int h, int qb, int t0, int wv, ...
;     ...
;         float pm_, alX = 1.f; ROWMAX(px0, px1, pm_);
;         if (__builtin_expect(__any(pm_ > THR), 0)) { const float dl_ = fmaxf(pm_, 0.f); SHIFT(px0, px1, dl_); alX = __builtin_amdgcn_exp2f(-dl_); }
.LBB0_1417:
	v_max3_f32 v128, v48, v64, v49
	v_max3_f32 v129, v65, v50, v66
	v_max3_f32 v130, v51, v67, v52
	v_max3_f32 v131, v68, v53, v69
	v_max3_f32 v128, v128, v54, v70
	v_max3_f32 v129, v129, v55, v71
	v_max3_f32 v130, v130, v56, v72
	v_max3_f32 v131, v131, v57, v73
	v_max3_f32 v128, v128, v58, v74
	v_max3_f32 v129, v129, v59, v75
	v_max3_f32 v130, v130, v60, v76
	v_max3_f32 v131, v131, v61, v77
	v_max3_f32 v128, v128, v62, v78
	v_max3_f32 v129, v129, v63, v79
	v_max3_f32 v128, v128, v129, v130
	v_max_f32_e32 v128, v128, v131
	v_mov_b32_e32 v129, v128
	s_nop 1
	v_permlane32_swap_b32_e32 v128, v129
	v_max_f32_e32 v129, v128, v129
	s_mov_b32 s4, 0x41000000
	v_cmp_lt_f32_e32 vcc, s4, v129
	v_mov_b32_e32 v128, 1.0
	s_cbranch_vccnz .LBB0_1429
